# grid barrier: non-leader workgroups poll the cross-XCD release word directly instead of their XCD leader's relay word (one atomic + one polling round trip less per seam); MLP-in ss loads prefetched
# speedup vs baseline: 1.0063x; 1.0037x over previous
.LBB0_114:
	s_or_b64 exec, exec, s[8:9]
	v_cvt_f32_u32_e32 v5, v3
	s_waitcnt vmcnt(0)
	v_readfirstlane_b32 s6, v4
	v_sub_u32_e32 v4, 0, v3
	v_rcp_iflag_f32_e32 v5, v5
	v_add_u32_e32 v6, s6, v2
	v_mul_f32_e32 v5, 0x4f7ffffe, v5
	v_cvt_u32_f32_e32 v5, v5
	v_mul_lo_u32 v2, v4, v5
	v_mul_hi_u32 v2, v5, v2
	v_add_u32_e32 v2, v5, v2
	v_mul_hi_u32 v2, v6, v2
	v_mul_lo_u32 v4, v2, v3
	v_sub_u32_e32 v4, v6, v4
	v_add_u32_e32 v5, 1, v2
	v_cmp_ge_u32_e32 vcc, v4, v3
	s_nop 1
	v_cndmask_b32_e32 v2, v2, v5, vcc
	v_sub_u32_e32 v5, v4, v3
	v_cndmask_b32_e32 v4, v4, v5, vcc
	v_add_u32_e32 v5, 1, v2
	v_cmp_ge_u32_e32 vcc, v4, v3
	v_add_u32_e32 v4, 1, v6
	s_nop 0
	v_cndmask_b32_e32 v2, v2, v5, vcc
	v_mul_lo_u32 v5, v3, v2
	v_add_u32_e32 v3, v5, v3
	v_cmp_ne_u32_e32 vcc, v4, v3
	s_and_saveexec_b64 s[6:7], vcc
	s_xor_b64 s[6:7], exec, s[6:7]
	s_cbranch_execz .LBB0_128
	s_waitcnt lgkmcnt(0)
	v_mov_b32_e32 v1, 0x74100
	global_load_dword v1, v1, s[72:73] offset:1024 sc1
	s_add_u32 s12, s72, 0x74500
	s_addc_u32 s13, s73, 0
	s_waitcnt vmcnt(0)
	v_cmp_eq_u32_e32 vcc, v1, v2
	s_and_saveexec_b64 s[8:9], vcc
	s_cbranch_execz .LBB0_127
	s_add_u32 s10, s72, 0x71200
	s_addc_u32 s11, s73, 0
	s_mov_b32 s24, 1
	s_mov_b64 s[14:15], 0
	v_mov_b32_e32 v1, 0
	s_branch .LBB0_118

.LBB0_585:
	s_or_b64 exec, exec, s[10:11]
	v_cvt_f32_u32_e32 v5, v3
	s_waitcnt vmcnt(0)
	v_readfirstlane_b32 s8, v4
	v_sub_u32_e32 v4, 0, v3
	v_rcp_iflag_f32_e32 v5, v5
	v_add_u32_e32 v6, s8, v2
	v_mul_f32_e32 v5, 0x4f7ffffe, v5
	v_cvt_u32_f32_e32 v5, v5
	v_mul_lo_u32 v2, v4, v5
	v_mul_hi_u32 v2, v5, v2
	v_add_u32_e32 v2, v5, v2
	v_mul_hi_u32 v2, v6, v2
	v_mul_lo_u32 v4, v2, v3
	v_sub_u32_e32 v4, v6, v4
	v_add_u32_e32 v5, 1, v2
	v_cmp_ge_u32_e32 vcc, v4, v3
	s_nop 1
	v_cndmask_b32_e32 v2, v2, v5, vcc
	v_sub_u32_e32 v5, v4, v3
	v_cndmask_b32_e32 v4, v4, v5, vcc
	v_add_u32_e32 v5, 1, v2
	v_cmp_ge_u32_e32 vcc, v4, v3
	v_add_u32_e32 v4, 1, v6
	s_nop 0
	v_cndmask_b32_e32 v2, v2, v5, vcc
	v_mul_lo_u32 v5, v3, v2
	v_add_u32_e32 v3, v5, v3
	v_cmp_ne_u32_e32 vcc, v4, v3
	s_and_saveexec_b64 s[8:9], vcc
	s_xor_b64 s[8:9], exec, s[8:9]
	s_cbranch_execz .LBB0_599
	s_waitcnt lgkmcnt(0)
	v_mov_b32_e32 v1, 0x74100
	global_load_dword v1, v1, s[72:73] offset:1024 sc1
	s_add_u32 s14, s72, 0x74500
	s_addc_u32 s15, s73, 0
	s_waitcnt vmcnt(0)
	v_cmp_eq_u32_e32 vcc, v1, v2
	s_and_saveexec_b64 s[10:11], vcc
	s_cbranch_execz .LBB0_598
	s_add_u32 s12, s72, 0x71200
	s_addc_u32 s13, s73, 0
	s_mov_b32 s26, 1
	s_mov_b64 s[16:17], 0
	v_mov_b32_e32 v1, 0
	s_branch .LBB0_589
